# grid barriers 12 and 15: leader L2 write-back dropped (all published stores of those phases are write-through)
# baseline (speedup 1.0000x reference)
.LBB0_1686:
	s_andn2_saveexec_b64 s[2:3], s[6:7]
	s_cbranch_execz .LBB0_1706
	s_mov_b64 s[6:7], exec
	s_waitcnt lgkmcnt(0)
	s_waitcnt vmcnt(0)
	buffer_inv sc1
	v_mbcnt_lo_u32_b32 v2, s6, 0
	v_mbcnt_hi_u32_b32 v2, s7, v2
	v_cmp_eq_u32_e32 vcc, 0, v2
	s_and_saveexec_b64 s[8:9], vcc
	s_cbranch_execz .LBB0_1689
	s_bcnt1_i32_b64 s2, s[6:7]
	v_mov_b32_e32 v3, 0x3000
	v_mov_b32_e32 v4, s2
	global_atomic_add v3, v3, v4, s[80:81] offset:1024 sc0
